# phase 4 conv_tile: staging loads batched (10 in flight, one wait) instead of serialized load-wait-write loop
# speedup vs baseline: 1.0216x; 1.0039x over previous
; DEV void conv_tile(const Params& p, int tile, char* smem) {
;     ...
;   __syncthreads();
;   for (int id = tid; id < 38 * 64; id += 256) {
;     const int row = id >> 6, cc = id & 63;
;     const int t = t0 - 15 + row;
;     uint4 v = make_uint4(0u, 0u, 0u, 0u);
;     if (t >= 0 && t < seq_len) v = *(const uint4*)(YG + (size_t)(seq_start + t) * 512 + cc * 8);
;     *(uint4*)(stg + row * 512 + cc * 8) = v;
;   }
.LBB0_781:
	s_cmpk_gt_i32 s16, 0x317
	s_mov_b64 s[6:7], -1
	s_cbranch_scc0 .LBB0_788
	s_cmpk_gt_u32 s16, 0x737
	s_cbranch_scc0 .LBB0_794
	s_add_i32 s6, s16, 0xfffff8c8
	s_and_b32 s7, s16, 7
	s_mul_i32 s17, s7, 0x108
	s_lshr_b32 s6, s6, 3
	s_add_i32 s17, s17, s6
	v_mov_b32_e32 v74, v195
	s_movk_i32 s6, 0x980
	s_movk_i32 s12, 0x2000
	s_waitcnt lgkmcnt(0)
	v_and_b32_e32 v70, 63, v74
	v_cmp_gt_i32_e32 vcc, s6, v74
	s_barrier
	s_and_saveexec_b64 s[6:7], vcc
	s_mov_b32 s34, 0x800000
	s_cbranch_execz .LBB0_789
	s_lshl_b32 s21, s17, 3
	s_cmpk_lt_u32 s17, 0x800
	s_movk_i32 s10, 0x7f00
	s_cselect_b32 s10, 0x2000, s10
	s_cselect_b32 s20, s12, 0x100
	s_and_b32 s10, s10, s21
	s_add_i32 s21, s21, -15
	s_sub_i32 s22, s21, s10
	v_readlane_b32 s10, v254, 8
	v_lshlrev_b32_e32 v6, 4, v70
	v_mov_b32_e32 v7, v1
	v_readlane_b32 s11, v254, 9
	s_nop 1
	v_lshl_add_u64 v[8:9], s[10:11], 0, v[6:7]
	v_lshrrev_b32_e32 v10, 6, v74
	v_add_u32_e32 v2, s21, v10
	v_ashrrev_i32_e32 v3, 31, v2
	v_readfirstlane_b32 s30, v10
	v_lshlrev_b64 v[2:3], 10, v[2:3]
	v_lshl_add_u64 v[2:3], v[8:9], 0, v[2:3]
	v_lshl_or_b32 v0, v10, 10, v6
	s_mov_b32 s38, 0x1000
	s_mov_b32 s39, 0
	s_add_i32 s31, s22, s30
	v_mov_b64_e32 v[12:13], 0
	v_mov_b64_e32 v[14:15], 0
	v_mov_b64_e32 v[16:17], 0
	v_mov_b64_e32 v[18:19], 0
	v_mov_b64_e32 v[20:21], 0
	v_mov_b64_e32 v[22:23], 0
	v_mov_b64_e32 v[24:25], 0
	v_mov_b64_e32 v[26:27], 0
	v_mov_b64_e32 v[28:29], 0
	v_mov_b64_e32 v[30:31], 0
	v_mov_b64_e32 v[32:33], 0
	v_mov_b64_e32 v[34:35], 0
	v_mov_b64_e32 v[36:37], 0
	v_mov_b64_e32 v[38:39], 0
	v_mov_b64_e32 v[40:41], 0
	v_mov_b64_e32 v[42:43], 0
	v_mov_b64_e32 v[44:45], 0
	v_mov_b64_e32 v[46:47], 0
	v_mov_b64_e32 v[48:49], 0
	v_mov_b64_e32 v[50:51], 0
	s_cmp_lt_u32 s31, s20
	s_cbranch_scc0 .Lcv_ld_skip_0
	global_load_dwordx4 v[12:15], v[2:3], off
.Lcv_ld_skip_0:
	v_lshl_add_u64 v[2:3], v[2:3], 0, s[38:39]
	s_add_i32 s31, s31, 4
	s_cmp_lt_u32 s31, s20
	s_cbranch_scc0 .Lcv_ld_skip_1
	global_load_dwordx4 v[16:19], v[2:3], off
.Lcv_ld_skip_1:
	v_lshl_add_u64 v[2:3], v[2:3], 0, s[38:39]
	s_add_i32 s31, s31, 4
	s_cmp_lt_u32 s31, s20
	s_cbranch_scc0 .Lcv_ld_skip_2
	global_load_dwordx4 v[20:23], v[2:3], off
.Lcv_ld_skip_2:
	v_lshl_add_u64 v[2:3], v[2:3], 0, s[38:39]
	s_add_i32 s31, s31, 4
	s_cmp_lt_u32 s31, s20
	s_cbranch_scc0 .Lcv_ld_skip_3
	global_load_dwordx4 v[24:27], v[2:3], off
.Lcv_ld_skip_3:
	v_lshl_add_u64 v[2:3], v[2:3], 0, s[38:39]
	s_add_i32 s31, s31, 4
	s_cmp_lt_u32 s31, s20
	s_cbranch_scc0 .Lcv_ld_skip_4
	global_load_dwordx4 v[28:31], v[2:3], off
.Lcv_ld_skip_4:
	v_lshl_add_u64 v[2:3], v[2:3], 0, s[38:39]
	s_add_i32 s31, s31, 4
	s_cmp_lt_u32 s31, s20
	s_cbranch_scc0 .Lcv_ld_skip_5
	global_load_dwordx4 v[32:35], v[2:3], off
.Lcv_ld_skip_5:
	v_lshl_add_u64 v[2:3], v[2:3], 0, s[38:39]
	s_add_i32 s31, s31, 4
	s_cmp_lt_u32 s31, s20
	s_cbranch_scc0 .Lcv_ld_skip_6
	global_load_dwordx4 v[36:39], v[2:3], off
.Lcv_ld_skip_6:
	v_lshl_add_u64 v[2:3], v[2:3], 0, s[38:39]
	s_add_i32 s31, s31, 4
	s_cmp_lt_u32 s31, s20
	s_cbranch_scc0 .Lcv_ld_skip_7
	global_load_dwordx4 v[40:43], v[2:3], off
.Lcv_ld_skip_7:
	v_lshl_add_u64 v[2:3], v[2:3], 0, s[38:39]
	s_add_i32 s31, s31, 4
	s_cmp_lt_u32 s31, s20
	s_cbranch_scc0 .Lcv_ld_skip_8
	global_load_dwordx4 v[44:47], v[2:3], off
.Lcv_ld_skip_8:
	v_lshl_add_u64 v[2:3], v[2:3], 0, s[38:39]
	s_add_i32 s31, s31, 4
	s_cmp_lt_u32 s31, s20
	s_cbranch_scc0 .Lcv_ld_skip_9
	s_cmp_lt_u32 s30, 2
	s_cbranch_scc0 .Lcv_ld_skip_9
	global_load_dwordx4 v[48:51], v[2:3], off
.Lcv_ld_skip_9:
	s_waitcnt vmcnt(0)
	ds_write_b128 v0, v[12:15]
	ds_write_b128 v0, v[16:19] offset:4096
	ds_write_b128 v0, v[20:23] offset:8192
	ds_write_b128 v0, v[24:27] offset:12288
	ds_write_b128 v0, v[28:31] offset:16384
	ds_write_b128 v0, v[32:35] offset:20480
	ds_write_b128 v0, v[36:39] offset:24576
	ds_write_b128 v0, v[40:43] offset:28672
	ds_write_b128 v0, v[44:47] offset:32768
	s_cmp_lt_u32 s30, 2
	s_cbranch_scc0 .LBB0_789
	ds_write_b128 v0, v[48:51] offset:36864
	s_branch .LBB0_789
